# adds neighbourhood-attention K and V fragment batch reads (LDS latency no longer serialised per MFMA)
# speedup vs baseline: 1.0286x; 1.0057x over previous
.LBB0_240:
	v_readlane_b32 s76, v252, 30
	v_readlane_b32 s77, v252, 31
	s_nop 4
	v_add3_u32 v66, s11, v155, v156
	s_andn2_b64 vcc, exec, s[76:77]
	v_cndmask_b32_e64 v67, 0, 1, s[76:77]
	v_cmp_ne_u32_e64 s[74:75], 1, v67
	v_add_u32_e32 v66, v66, v144
	ds_read_b64_tr_b16 v[174:175], v66 offset:8192
	ds_read_b64_tr_b16 v[176:177], v66 offset:8704
	ds_read_b64_tr_b16 v[178:179], v66 offset:9216
	ds_read_b64_tr_b16 v[180:181], v66 offset:9728
	ds_read_b64_tr_b16 v[182:183], v66 offset:10240
	ds_read_b64_tr_b16 v[184:185], v66 offset:10752
	ds_read_b64_tr_b16 v[186:187], v66 offset:11264
	ds_read_b64_tr_b16 v[188:189], v66 offset:11776
	ds_read_b64_tr_b16 v[190:191], v66 offset:12288
	ds_read_b64_tr_b16 v[192:193], v66 offset:12800
	ds_read_b64_tr_b16 v[194:195], v66 offset:13312
	ds_read_b64_tr_b16 v[196:197], v66 offset:13824
	s_cbranch_vccnz .LBB0_242
	s_waitcnt lgkmcnt(10)
	v_mfma_f32_32x32x16_bf16 v[16:31], v[174:177], v[114:117], v[16:31]
.LBB0_242:
	v_readlane_b32 vcc_lo, v252, 32
	v_readlane_b32 vcc_hi, v252, 33
	s_waitcnt lgkmcnt(8)
	v_mfma_f32_32x32x16_bf16 v[16:31], v[178:181], v[130:133], v[16:31]
	ds_read_b64_tr_b16 v[198:199], v66 offset:14336
	ds_read_b64_tr_b16 v[200:201], v66 offset:14848
	ds_read_b64_tr_b16 v[202:203], v66 offset:15360
	ds_read_b64_tr_b16 v[204:205], v66 offset:15872
	v_cndmask_b32_e64 v67, 0, 1, vcc
	v_cmp_ne_u32_e64 s[76:77], 1, v67
	s_andn2_b64 vcc, exec, vcc
	s_waitcnt lgkmcnt(10)
	v_mfma_f32_32x32x16_bf16 v[16:31], v[182:185], v[126:129], v[16:31]
	s_cbranch_vccnz .LBB0_244
	s_waitcnt lgkmcnt(8)
	v_mfma_f32_32x32x16_bf16 v[16:31], v[186:189], v[134:137], v[16:31]
.LBB0_244:
	s_and_b64 vcc, exec, s[74:75]
	s_cbranch_vccnz .LBB0_246
	s_waitcnt lgkmcnt(6)
	v_mfma_f32_32x32x16_bf16 v[0:15], v[190:193], v[114:117], v[0:15]
.LBB0_246:
	s_and_b64 vcc, exec, s[76:77]
	s_waitcnt lgkmcnt(4)
	s_nop 5
	v_mfma_f32_32x32x16_bf16 v[0:15], v[194:197], v[130:133], v[0:15]
	s_waitcnt lgkmcnt(2)
	v_mfma_f32_32x32x16_bf16 v[0:15], v[198:201], v[126:129], v[0:15]
	s_cbranch_vccnz .LBB0_248
	s_waitcnt lgkmcnt(0)
	v_mfma_f32_32x32x16_bf16 v[0:15], v[202:205], v[134:137], v[0:15]
